# static s_setprio 1 moved from waves 4-7 to waves 0-3 (A/B of which half gets the raise)
# speedup vs baseline: 1.0136x; 1.0136x over previous
; __device__ __forceinline__ int otid() { int t = threadIdx.x; asm volatile("" : "+v"(t)); return t; }
; __global__ void __launch_bounds__(512) fwd_kernel(KArgs A0) {
;     ...
;         const int tid_ = otid(); const int lane = tid_ & 63, wave = __builtin_amdgcn_readfirstlane(tid_ >> 6);
;         const KArgs __attribute__((address_space(4)))* ap_ = (const KArgs __attribute__((address_space(4)))*)__builtin_amdgcn_kernarg_segment_ptr();
;         asm volatile("" : "+s"(ap_));
;         const KArgs& A = *(const KArgs*)ap_;
;         unsigned char* ws = A.ws;
.LBB0_22:
	v_writelane_b32 v255, s40, 4
	v_mov_b32_e32 v191, v184
	s_mov_b64 s[56:57], s[44:45]
	v_writelane_b32 v255, s41, 5
	v_writelane_b32 v255, s42, 6
	s_waitcnt lgkmcnt(0)
	s_load_dwordx2 s[94:95], s[56:57], 0x168
	v_readfirstlane_b32 s2, v191
	v_writelane_b32 v255, s43, 7
	s_ashr_i32 s2, s2, 6
	v_writelane_b32 v255, s2, 8
	s_cmp_ge_u32 s2, 4
	s_cbranch_scc1 .Lprio_skip
	s_setprio 1
